# combination of v124 with the pipelined final row-norm, permlane softmax reductions and two-accumulator fused dots
# baseline (speedup 1.0000x reference)
; __device__ __forceinline__ void nat_phase(const Params& p, float* ldsf, int wave0, int nwaves) {
;     ...
;             f32x4 sc[8][2];
; #pragma unroll
;             for (int i = 0; i < 8; ++i)
; #pragma unroll
;                 for (int hf = 0; hf < 2; ++hf) { const u16* kp = Kb + (size_t)(i * 64 + cs0 + (l15 >> 2) * 8 + hf * 4 + (l15 & 3)) * RW + lq * 8;
;                     const bf16x8 a0 = *(const bf16x8*)kp, a1 = *(const bf16x8*)(kp + 32); f32x4 z = {0.f, 0.f, 0.f, 0.f};
;                     z = __builtin_amdgcn_mfma_f32_16x16x32_bf16(a0, bq0, z, 0, 0, 0); z = __builtin_amdgcn_mfma_f32_16x16x32_bf16(a1, bq1, z, 0, 0, 0); sc[i][hf] = z; }
.Lmy_nat_p2j:
	s_waitcnt lgkmcnt(0)
	ds_read_b128 v[0:3], v48 offset:0
	ds_read_b128 v[4:7], v48 offset:1024
	ds_read_b128 v[8:11], v48 offset:2048
	ds_read_b128 v[12:15], v48 offset:3072
	ds_read_b128 v[16:19], v48 offset:4096
	ds_read_b128 v[20:23], v48 offset:5120
	ds_read_b128 v[24:27], v48 offset:6144
	ds_read_b128 v[28:31], v48 offset:7168
	ds_read_b128 v[32:35], v48 offset:8192
	ds_read_b128 v[36:39], v48 offset:9216
	ds_read_b128 v[40:43], v48 offset:10240
	ds_read_b128 v[44:47], v48 offset:11264
	s_waitcnt lgkmcnt(11)
	v_mfma_f32_16x16x32_bf16 v[128:131], v[0:3], v[192:195], v[128:131]
	ds_read_b128 v[0:3], v48 offset:12288
	s_waitcnt lgkmcnt(11)
	v_mfma_f32_16x16x32_bf16 v[128:131], v[4:7], v[196:199], v[128:131]
	ds_read_b128 v[4:7], v48 offset:13312
	s_waitcnt lgkmcnt(11)
	v_mfma_f32_16x16x32_bf16 v[132:135], v[8:11], v[192:195], v[132:135]
	ds_read_b128 v[8:11], v48 offset:14336
	s_waitcnt lgkmcnt(11)
	v_mfma_f32_16x16x32_bf16 v[132:135], v[12:15], v[196:199], v[132:135]
	ds_read_b128 v[12:15], v48 offset:15360
	s_waitcnt lgkmcnt(11)
	v_mfma_f32_16x16x32_bf16 v[136:139], v[16:19], v[192:195], v[136:139]
	ds_read_b128 v[16:19], v48 offset:16384
	s_waitcnt lgkmcnt(11)
	v_mfma_f32_16x16x32_bf16 v[136:139], v[20:23], v[196:199], v[136:139]
	ds_read_b128 v[20:23], v48 offset:17408
	s_waitcnt lgkmcnt(11)
	v_mfma_f32_16x16x32_bf16 v[140:143], v[24:27], v[192:195], v[140:143]
	ds_read_b128 v[24:27], v48 offset:18432
	s_waitcnt lgkmcnt(11)
	v_mfma_f32_16x16x32_bf16 v[140:143], v[28:31], v[196:199], v[140:143]
	ds_read_b128 v[28:31], v48 offset:19456
	s_waitcnt lgkmcnt(11)
	v_mfma_f32_16x16x32_bf16 v[144:147], v[32:35], v[192:195], v[144:147]
	ds_read_b128 v[32:35], v48 offset:20480
	s_waitcnt lgkmcnt(11)
	v_mfma_f32_16x16x32_bf16 v[144:147], v[36:39], v[196:199], v[144:147]
	ds_read_b128 v[36:39], v48 offset:21504
	s_waitcnt lgkmcnt(11)
	v_mfma_f32_16x16x32_bf16 v[148:151], v[40:43], v[192:195], v[148:151]
	ds_read_b128 v[40:43], v48 offset:22528
	s_waitcnt lgkmcnt(11)
	v_mfma_f32_16x16x32_bf16 v[148:151], v[44:47], v[196:199], v[148:151]
	ds_read_b128 v[44:47], v48 offset:23552
	s_waitcnt lgkmcnt(11)
	v_mfma_f32_16x16x32_bf16 v[152:155], v[0:3], v[192:195], v[152:155]
	ds_read_b128 v[0:3], v48 offset:24576
	s_waitcnt lgkmcnt(11)
	v_mfma_f32_16x16x32_bf16 v[152:155], v[4:7], v[196:199], v[152:155]
	ds_read_b128 v[4:7], v48 offset:25600
	s_waitcnt lgkmcnt(11)
	v_mfma_f32_16x16x32_bf16 v[156:159], v[8:11], v[192:195], v[156:159]
	ds_read_b128 v[8:11], v48 offset:26624
	s_waitcnt lgkmcnt(11)
	v_mfma_f32_16x16x32_bf16 v[156:159], v[12:15], v[196:199], v[156:159]
	ds_read_b128 v[12:15], v48 offset:27648
	s_waitcnt lgkmcnt(11)
	v_mfma_f32_16x16x32_bf16 v[160:163], v[16:19], v[192:195], v[160:163]
	ds_read_b128 v[16:19], v48 offset:28672
	s_waitcnt lgkmcnt(11)
	v_mfma_f32_16x16x32_bf16 v[160:163], v[20:23], v[196:199], v[160:163]
	ds_read_b128 v[20:23], v48 offset:29696
	s_waitcnt lgkmcnt(11)
	v_mfma_f32_16x16x32_bf16 v[164:167], v[24:27], v[192:195], v[164:167]
	ds_read_b128 v[24:27], v48 offset:30720
	s_waitcnt lgkmcnt(11)
	v_mfma_f32_16x16x32_bf16 v[164:167], v[28:31], v[196:199], v[164:167]
	ds_read_b128 v[28:31], v48 offset:31744
	s_waitcnt lgkmcnt(11)
	v_mfma_f32_16x16x32_bf16 v[168:171], v[32:35], v[192:195], v[168:171]
	s_waitcnt lgkmcnt(10)
	v_mfma_f32_16x16x32_bf16 v[168:171], v[36:39], v[196:199], v[168:171]
	s_waitcnt lgkmcnt(9)
	v_mfma_f32_16x16x32_bf16 v[172:175], v[40:43], v[192:195], v[172:175]
	s_waitcnt lgkmcnt(8)
	v_mfma_f32_16x16x32_bf16 v[172:175], v[44:47], v[196:199], v[172:175]
	s_waitcnt lgkmcnt(7)
	v_mfma_f32_16x16x32_bf16 v[176:179], v[0:3], v[192:195], v[176:179]
	s_waitcnt lgkmcnt(6)
	v_mfma_f32_16x16x32_bf16 v[176:179], v[4:7], v[196:199], v[176:179]
	s_waitcnt lgkmcnt(5)
	v_mfma_f32_16x16x32_bf16 v[180:183], v[8:11], v[192:195], v[180:183]
	s_waitcnt lgkmcnt(4)
	v_mfma_f32_16x16x32_bf16 v[180:183], v[12:15], v[196:199], v[180:183]
	s_waitcnt lgkmcnt(3)
	v_mfma_f32_16x16x32_bf16 v[184:187], v[16:19], v[192:195], v[184:187]
	s_waitcnt lgkmcnt(2)
	v_mfma_f32_16x16x32_bf16 v[184:187], v[20:23], v[196:199], v[184:187]
	s_waitcnt lgkmcnt(1)
	v_mfma_f32_16x16x32_bf16 v[188:191], v[24:27], v[192:195], v[188:191]
	s_waitcnt lgkmcnt(0)
; __device__ __forceinline__ void nat_phase(const Params& p, float* ldsf, int wave0, int nwaves) {
;     ...
;             float mx = -1e30f;
; #pragma unroll
;             for (int i = 0; i < 8; ++i)
; #pragma unroll
;                 for (int hf = 0; hf < 2; ++hf)
; #pragma unroll
;                     for (int j = 0; j < 4; ++j) { const int kc = cs0 + lq * 8 + hf * 4 + j; const bool valid = (kc >= csq) && (kc < csq + 16); const int bc = valid ? (kc - c + 15) : 0;
;                         const float s = valid ? sc[i][hf][j] * 0.125f + tb[i * 31 + bc] : -1e30f; sc[i][hf][j] = s; mx = fmaxf(mx, s); }
;             mx = fmaxf(mx, __shfl_xor(mx, 16)); mx = fmaxf(mx, __shfl_xor(mx, 32));
;             float sum = 0.f;
; #pragma unroll
;             for (int i = 0; i < 8; ++i)
; #pragma unroll
;                 for (int hf = 0; hf < 2; ++hf)
; #pragma unroll
;                     for (int j = 0; j < 4; ++j) { const float e = __expf(sc[i][hf][j] - mx); sc[i][hf][j] = e; sum += e; }
	v_mfma_f32_16x16x32_bf16 v[188:191], v[28:31], v[196:199], v[188:191]
	s_lshl_b32 s84, s82, 11
	s_add_u32 s84, s84, s79
	buffer_load_dwordx2 v[216:217], v227, s[68:71], s84 offen offset:0
	buffer_load_dwordx2 v[218:219], v227, s[68:71], s84 offen offset:32
	buffer_load_dwordx2 v[220:221], v227, s[68:71], s84 offen offset:64
	buffer_load_dwordx2 v[222:223], v227, s[68:71], s84 offen offset:96
	v_max3_f32 v239, v128, v129, v130
	v_max3_f32 v239, v239, v131, v132
	v_max3_f32 v239, v239, v133, v134
	v_max3_f32 v239, v239, v135, v136
	v_max3_f32 v239, v239, v137, v138
	v_max3_f32 v239, v239, v139, v140
	v_max3_f32 v239, v239, v141, v142
	v_max3_f32 v239, v239, v143, v144
	v_max3_f32 v239, v239, v145, v146
	v_max3_f32 v239, v239, v147, v148
	v_max3_f32 v239, v239, v149, v150
	v_max3_f32 v239, v239, v151, v152
	v_max3_f32 v239, v239, v153, v154
	v_max3_f32 v239, v239, v155, v156
	v_max3_f32 v239, v239, v157, v158
	v_max3_f32 v239, v239, v159, v160
	v_max3_f32 v239, v239, v161, v162
	v_max3_f32 v239, v239, v163, v164
	v_max3_f32 v239, v239, v165, v166
	v_max3_f32 v239, v239, v167, v168
	v_max3_f32 v239, v239, v169, v170
	v_max3_f32 v239, v239, v171, v172
	v_max3_f32 v239, v239, v173, v174
	v_max3_f32 v239, v239, v175, v176
	v_max3_f32 v239, v239, v177, v178
	v_max3_f32 v239, v239, v179, v180
	v_max3_f32 v239, v239, v181, v182
	v_max3_f32 v239, v239, v183, v184
	v_max3_f32 v239, v239, v185, v186
	v_max3_f32 v239, v239, v187, v188
	v_max3_f32 v239, v239, v189, v190
	v_max_f32_e32 v239, v239, v191
	v_mov_b32_e32 v242, v239
	s_nop 1
	v_permlane16_swap_b32 v242, v239
	v_max_f32_e32 v239, v239, v242
	v_mov_b32_e32 v242, v239
	s_nop 1
	v_permlane32_swap_b32 v242, v239
	v_max_f32_e32 v239, v239, v242
	v_mul_f32_e64 v242, -v239, v252
	v_mov_b32_e32 v243, v242
	v_pk_fma_f32 v[128:129], v[128:129], v[252:253], v[242:243]
	v_pk_fma_f32 v[130:131], v[130:131], v[252:253], v[242:243]
	v_pk_fma_f32 v[132:133], v[132:133], v[252:253], v[242:243]
	v_pk_fma_f32 v[134:135], v[134:135], v[252:253], v[242:243]
	v_pk_fma_f32 v[136:137], v[136:137], v[252:253], v[242:243]
	v_pk_fma_f32 v[138:139], v[138:139], v[252:253], v[242:243]
	v_pk_fma_f32 v[140:141], v[140:141], v[252:253], v[242:243]
	v_pk_fma_f32 v[142:143], v[142:143], v[252:253], v[242:243]
	v_pk_fma_f32 v[144:145], v[144:145], v[252:253], v[242:243]
	v_pk_fma_f32 v[146:147], v[146:147], v[252:253], v[242:243]
	v_pk_fma_f32 v[148:149], v[148:149], v[252:253], v[242:243]
	v_pk_fma_f32 v[150:151], v[150:151], v[252:253], v[242:243]
	v_pk_fma_f32 v[152:153], v[152:153], v[252:253], v[242:243]
	v_pk_fma_f32 v[154:155], v[154:155], v[252:253], v[242:243]
	v_pk_fma_f32 v[156:157], v[156:157], v[252:253], v[242:243]
	v_pk_fma_f32 v[158:159], v[158:159], v[252:253], v[242:243]
	v_pk_fma_f32 v[160:161], v[160:161], v[252:253], v[242:243]
	v_pk_fma_f32 v[162:163], v[162:163], v[252:253], v[242:243]
	v_pk_fma_f32 v[164:165], v[164:165], v[252:253], v[242:243]
	v_pk_fma_f32 v[166:167], v[166:167], v[252:253], v[242:243]
	v_pk_fma_f32 v[168:169], v[168:169], v[252:253], v[242:243]
	v_pk_fma_f32 v[170:171], v[170:171], v[252:253], v[242:243]
	v_pk_fma_f32 v[172:173], v[172:173], v[252:253], v[242:243]
	v_pk_fma_f32 v[174:175], v[174:175], v[252:253], v[242:243]
	v_pk_fma_f32 v[176:177], v[176:177], v[252:253], v[242:243]
	v_pk_fma_f32 v[178:179], v[178:179], v[252:253], v[242:243]
	v_pk_fma_f32 v[180:181], v[180:181], v[252:253], v[242:243]
	v_pk_fma_f32 v[182:183], v[182:183], v[252:253], v[242:243]
	v_pk_fma_f32 v[184:185], v[184:185], v[252:253], v[242:243]
	v_pk_fma_f32 v[186:187], v[186:187], v[252:253], v[242:243]
	v_pk_fma_f32 v[188:189], v[188:189], v[252:253], v[242:243]
	v_pk_fma_f32 v[190:191], v[190:191], v[252:253], v[242:243]
	v_exp_f32_e32 v128, v128
	v_exp_f32_e32 v129, v129
	v_exp_f32_e32 v130, v130
	v_exp_f32_e32 v131, v131
	v_exp_f32_e32 v132, v132
	v_exp_f32_e32 v133, v133
	v_exp_f32_e32 v134, v134
	v_exp_f32_e32 v135, v135
	v_exp_f32_e32 v136, v136
	v_exp_f32_e32 v137, v137
	v_exp_f32_e32 v138, v138
	v_exp_f32_e32 v139, v139
	v_exp_f32_e32 v140, v140
	v_exp_f32_e32 v141, v141
	v_exp_f32_e32 v142, v142
	v_exp_f32_e32 v143, v143
	v_exp_f32_e32 v144, v144
	v_exp_f32_e32 v145, v145
	v_exp_f32_e32 v146, v146
	v_exp_f32_e32 v147, v147
	v_exp_f32_e32 v148, v148
	v_exp_f32_e32 v149, v149
	v_exp_f32_e32 v150, v150
	v_exp_f32_e32 v151, v151
	v_exp_f32_e32 v152, v152
	v_exp_f32_e32 v153, v153
	v_exp_f32_e32 v154, v154
	v_exp_f32_e32 v155, v155
	v_exp_f32_e32 v156, v156
	v_exp_f32_e32 v157, v157
	v_exp_f32_e32 v158, v158
	v_exp_f32_e32 v159, v159
	v_exp_f32_e32 v160, v160
	v_exp_f32_e32 v161, v161
	v_exp_f32_e32 v162, v162
	v_exp_f32_e32 v163, v163
	v_exp_f32_e32 v164, v164
	v_exp_f32_e32 v165, v165
	v_exp_f32_e32 v166, v166
	v_exp_f32_e32 v167, v167
	v_exp_f32_e32 v168, v168
	v_exp_f32_e32 v169, v169
	v_exp_f32_e32 v170, v170
	v_exp_f32_e32 v171, v171
	v_exp_f32_e32 v172, v172
	v_exp_f32_e32 v173, v173
	v_exp_f32_e32 v174, v174
	v_exp_f32_e32 v175, v175
	v_exp_f32_e32 v176, v176
; __device__ __forceinline__ unsigned cvt_pk_bf16(float lo, float hi) { unsigned r; asm volatile("v_cvt_pk_bf16_f32 %0, %1, %2" : "=v"(r) : "v"(lo), "v"(hi)); return r; }
; __device__ __forceinline__ void nat_phase(const Params& p, float* ldsf, int wave0, int nwaves) {
;     ...
;                     for (int j = 0; j < 4; ++j) { const float e = __expf(sc[i][hf][j] - mx); sc[i][hf][j] = e; sum += e; }
;             sum += __shfl_xor(sum, 16); sum += __shfl_xor(sum, 32);
;             const float inv = 1.0f / sum;
;             f32x4 o[4];
; #pragma unroll
;             for (int mt = 0; mt < 4; ++mt) o[mt] = (f32x4){0.f, 0.f, 0.f, 0.f};
; #pragma unroll
;             for (int i = 0; i < 8; ++i) {
;                 u32x4 pw; pw.x = cvt_pk_bf16(sc[i][0][0] * inv, sc[i][0][1] * inv); pw.y = cvt_pk_bf16(sc[i][0][2] * inv, sc[i][0][3] * inv);
;                 pw.z = cvt_pk_bf16(sc[i][1][0] * inv, sc[i][1][1] * inv); pw.w = cvt_pk_bf16(sc[i][1][2] * inv, sc[i][1][3] * inv);
;                 const bf16x8 bp = __builtin_bit_cast(bf16x8, pw);
	v_exp_f32_e32 v177, v177
	v_exp_f32_e32 v178, v178
	v_exp_f32_e32 v179, v179
	v_exp_f32_e32 v180, v180
	v_exp_f32_e32 v181, v181
	v_exp_f32_e32 v182, v182
	v_exp_f32_e32 v183, v183
	v_exp_f32_e32 v184, v184
	v_exp_f32_e32 v185, v185
	v_exp_f32_e32 v186, v186
	v_exp_f32_e32 v187, v187
	v_exp_f32_e32 v188, v188
	v_exp_f32_e32 v189, v189
	v_exp_f32_e32 v190, v190
	v_exp_f32_e32 v191, v191
	s_nop 0
	v_pk_add_f32 v[244:245], v[128:129], v[130:131]
	v_pk_add_f32 v[246:247], v[132:133], v[134:135]
	v_pk_add_f32 v[244:245], v[244:245], v[136:137]
	v_pk_add_f32 v[246:247], v[246:247], v[138:139]
	v_pk_add_f32 v[244:245], v[244:245], v[140:141]
	v_pk_add_f32 v[246:247], v[246:247], v[142:143]
	v_pk_add_f32 v[244:245], v[244:245], v[144:145]
	v_pk_add_f32 v[246:247], v[246:247], v[146:147]
	v_pk_add_f32 v[244:245], v[244:245], v[148:149]
	v_pk_add_f32 v[246:247], v[246:247], v[150:151]
	v_pk_add_f32 v[244:245], v[244:245], v[152:153]
	v_pk_add_f32 v[246:247], v[246:247], v[154:155]
	v_pk_add_f32 v[244:245], v[244:245], v[156:157]
	v_pk_add_f32 v[246:247], v[246:247], v[158:159]
	v_pk_add_f32 v[244:245], v[244:245], v[160:161]
	v_pk_add_f32 v[246:247], v[246:247], v[162:163]
	v_pk_add_f32 v[244:245], v[244:245], v[164:165]
	v_pk_add_f32 v[246:247], v[246:247], v[166:167]
	v_pk_add_f32 v[244:245], v[244:245], v[168:169]
	v_pk_add_f32 v[246:247], v[246:247], v[170:171]
	v_pk_add_f32 v[244:245], v[244:245], v[172:173]
	v_pk_add_f32 v[246:247], v[246:247], v[174:175]
	v_pk_add_f32 v[244:245], v[244:245], v[176:177]
	v_pk_add_f32 v[246:247], v[246:247], v[178:179]
	v_pk_add_f32 v[244:245], v[244:245], v[180:181]
	v_pk_add_f32 v[246:247], v[246:247], v[182:183]
	v_pk_add_f32 v[244:245], v[244:245], v[184:185]
	v_pk_add_f32 v[246:247], v[246:247], v[186:187]
	v_pk_add_f32 v[244:245], v[244:245], v[188:189]
	v_pk_add_f32 v[246:247], v[246:247], v[190:191]
	v_pk_add_f32 v[244:245], v[244:245], v[246:247]
	v_add_f32_e32 v240, v244, v245
	v_mov_b32_e32 v242, v240
	s_nop 1
	v_permlane16_swap_b32 v242, v240
	v_add_f32_e32 v240, v240, v242
	v_mov_b32_e32 v242, v240
	s_nop 1
	v_permlane32_swap_b32 v242, v240
	v_add_f32_e32 v240, v240, v242
	v_rcp_f32_e32 v242, v240
	s_nop 0
	v_mov_b32_e32 v243, v242
	v_pk_mul_f32 v[128:129], v[128:129], v[242:243]
	v_pk_mul_f32 v[130:131], v[130:131], v[242:243]
	v_pk_mul_f32 v[132:133], v[132:133], v[242:243]
	v_pk_mul_f32 v[134:135], v[134:135], v[242:243]
	v_pk_mul_f32 v[136:137], v[136:137], v[242:243]
	v_pk_mul_f32 v[138:139], v[138:139], v[242:243]
	v_pk_mul_f32 v[140:141], v[140:141], v[242:243]
	v_pk_mul_f32 v[142:143], v[142:143], v[242:243]
	v_pk_mul_f32 v[144:145], v[144:145], v[242:243]
	v_pk_mul_f32 v[146:147], v[146:147], v[242:243]
	v_pk_mul_f32 v[148:149], v[148:149], v[242:243]
	v_pk_mul_f32 v[150:151], v[150:151], v[242:243]
	v_pk_mul_f32 v[152:153], v[152:153], v[242:243]
	v_pk_mul_f32 v[154:155], v[154:155], v[242:243]
	v_pk_mul_f32 v[156:157], v[156:157], v[242:243]
	v_pk_mul_f32 v[158:159], v[158:159], v[242:243]
	v_pk_mul_f32 v[160:161], v[160:161], v[242:243]
	v_pk_mul_f32 v[162:163], v[162:163], v[242:243]
	v_pk_mul_f32 v[164:165], v[164:165], v[242:243]
	v_pk_mul_f32 v[166:167], v[166:167], v[242:243]
	v_pk_mul_f32 v[168:169], v[168:169], v[242:243]
	v_pk_mul_f32 v[170:171], v[170:171], v[242:243]
	v_pk_mul_f32 v[172:173], v[172:173], v[242:243]
	v_pk_mul_f32 v[174:175], v[174:175], v[242:243]
	v_pk_mul_f32 v[176:177], v[176:177], v[242:243]
	v_pk_mul_f32 v[178:179], v[178:179], v[242:243]
	v_pk_mul_f32 v[180:181], v[180:181], v[242:243]
	v_pk_mul_f32 v[182:183], v[182:183], v[242:243]
	v_pk_mul_f32 v[184:185], v[184:185], v[242:243]
	v_pk_mul_f32 v[186:187], v[186:187], v[242:243]
	v_pk_mul_f32 v[188:189], v[188:189], v[242:243]
	v_pk_mul_f32 v[190:191], v[190:191], v[242:243]
	v_cvt_pk_bf16_f32 v128, v128, v129
	v_cvt_pk_bf16_f32 v129, v130, v131
	v_cvt_pk_bf16_f32 v130, v132, v133
	v_cvt_pk_bf16_f32 v131, v134, v135
	v_cvt_pk_bf16_f32 v136, v136, v137
	v_cvt_pk_bf16_f32 v137, v138, v139
	v_cvt_pk_bf16_f32 v138, v140, v141
	v_cvt_pk_bf16_f32 v139, v142, v143
	v_cvt_pk_bf16_f32 v144, v144, v145
	v_cvt_pk_bf16_f32 v145, v146, v147
	v_cvt_pk_bf16_f32 v146, v148, v149
	v_cvt_pk_bf16_f32 v147, v150, v151
	v_cvt_pk_bf16_f32 v152, v152, v153
	v_cvt_pk_bf16_f32 v153, v154, v155
	v_cvt_pk_bf16_f32 v154, v156, v157
	v_cvt_pk_bf16_f32 v155, v158, v159
	v_cvt_pk_bf16_f32 v160, v160, v161
	v_cvt_pk_bf16_f32 v161, v162, v163
	v_cvt_pk_bf16_f32 v162, v164, v165
	v_cvt_pk_bf16_f32 v163, v166, v167
	v_cvt_pk_bf16_f32 v168, v168, v169
	v_cvt_pk_bf16_f32 v169, v170, v171
	v_cvt_pk_bf16_f32 v170, v172, v173
	v_cvt_pk_bf16_f32 v171, v174, v175
	v_cvt_pk_bf16_f32 v176, v176, v177
	v_cvt_pk_bf16_f32 v177, v178, v179
	v_cvt_pk_bf16_f32 v178, v180, v181
	v_cvt_pk_bf16_f32 v179, v182, v183
	v_cvt_pk_bf16_f32 v184, v184, v185
	v_cvt_pk_bf16_f32 v185, v186, v187
	v_cvt_pk_bf16_f32 v186, v188, v189
	v_cvt_pk_bf16_f32 v187, v190, v191
	s_cmp_lt_u32 s1, 4
	s_cbranch_scc1 .Lmy_nat_p3j
	s_waitcnt vmcnt(4)
